# phase C K-loop: LDS-DMA staging loads moved from the first quarter-step into the second, scalar M0 values
# baseline (speedup 1.0000x reference)
; #define TIDX512 launder_i((int)threadIdx.x)
; __device__ __forceinline__ void glds16(const bf16_t* g, char* l) { __builtin_amdgcn_global_load_lds((const unsigned*)g, (unsigned*)l, 16, 0, 0); }
; __device__ __forceinline__ void gemm_issue(const GemmSrc& g, int kt, int s, char* lds) {
;     const int tid = TIDX512, lane = tid & 63, wave = tid >> 6;
;     char* xdst = lds + s * 65536 + wave * 4096 + lane * 16;
;     char* wdst = xdst + 32768;
; #pragma unroll
;     for (int i = 0; i < 4; i++) {
;         const int d = (i & 1) ? g.dsw : 0;
;         glds16(g.xsrc + (size_t)i * 8 * g.ldx + kt * 64 + d, xdst + i * 1024);
;         glds16(g.wsrc + (size_t)i * 8 * g.ldw + kt * 64 + d, wdst + i * 1024);
;     }
; }
; __device__ __forceinline__ void gemm_prologue(const GemmSrc& g, char* lds) { gemm_issue(g, 0, 0, lds); }
; __device__ __forceinline__ void zero_acc(f32x4 (&acc)[8][4]) {
; #pragma unroll
;     for (int a = 0; a < 8; a++)
; #pragma unroll
;         for (int b = 0; b < 4; b++) acc[a][b] = (f32x4){0.f, 0.f, 0.f, 0.f};
; }
.LBB0_298:
	s_andn2_b64 vcc, exec, s[8:9]
	s_mov_b64 s[8:9], -1
	s_cbranch_vccnz .LBB0_290
	v_mov_b32_e32 v0, v158
	s_lshl_b32 s82, s74, 8
	v_ashrrev_i32_e32 v1, 1, v0
	v_and_b32_e32 v12, 0xffffffe0, v1
	v_bfe_u32 v1, v0, 4, 2
	v_and_b32_e32 v3, 7, v0
	v_bitop3_b32 v4, v1, v0, 7 bitop3:0x78
	v_bitop3_b32 v5, v1, v3, 4 bitop3:0x36
	v_lshlrev_b32_e32 v128, 4, v4
	v_sub_u32_e32 v4, v5, v4
	v_mov_b32_e32 v5, v158
	v_bfe_u32 v13, v0, 3, 3
	v_or_b32_e32 v2, v12, v13
	v_lshlrev_b32_e32 v6, 6, v5
	v_lshlrev_b32_e32 v5, 4, v5
	s_lshl_b32 s44, s75, 8
	v_add_u32_e32 v0, s82, v2
	v_and_b32_e32 v5, 0x3f0, v5
	v_ashrrev_i32_e32 v1, 31, v0
	v_add_u32_e32 v2, s44, v2
	v_and_or_b32 v14, v6, s51, v5
	v_lshlrev_b64 v[0:1], 11, v[0:1]
	v_ashrrev_i32_e32 v3, 31, v2
	v_lshlrev_b32_e32 v4, 3, v4
	v_add_u32_e32 v5, 0x8000, v14
	v_readfirstlane_b32 s0, v14
	v_lshl_add_u64 v[0:1], s[14:15], 0, v[0:1]
	v_lshlrev_b64 v[2:3], 11, v[2:3]
	s_mov_b32 m0, s0
	v_readfirstlane_b32 s0, v5
	v_ashrrev_i32_e32 v5, 31, v4
	v_lshl_add_u64 v[0:1], v[0:1], 0, v[128:129]
	v_lshl_add_u64 v[2:3], s[16:17], 0, v[2:3]
	v_lshlrev_b64 v[4:5], 1, v[4:5]
	v_or_b32_e32 v10, 0x400, v14
	v_lshl_add_u64 v[2:3], v[2:3], 0, v[128:129]
	global_load_lds_dwordx4 v[0:1], off
	s_mov_b32 m0, s0
	v_lshl_add_u64 v[6:7], v[0:1], 0, v[4:5]
	v_readfirstlane_b32 s0, v10
	global_load_lds_dwordx4 v[2:3], off
	v_lshl_add_u64 v[8:9], v[6:7], 0, s[20:21]
	s_mov_b32 m0, s0
	v_add_u32_e32 v15, 0x8400, v14
	global_load_lds_dwordx4 v[8:9], off
	v_lshl_add_u64 v[8:9], v[2:3], 0, v[4:5]
	v_readfirstlane_b32 s0, v15
	v_lshl_add_u64 v[10:11], v[8:9], 0, s[20:21]
	s_mov_b32 m0, s0
	v_lshl_add_u64 v[0:1], v[0:1], 0, s[22:23]
	global_load_lds_dwordx4 v[10:11], off
	v_or_b32_e32 v10, 0x800, v14
	s_mov_b64 s[8:9], 0
	v_readfirstlane_b32 s0, v10
	s_mov_b32 m0, s0
	s_nop 0
	global_load_lds_dwordx4 v[0:1], off
	v_lshl_add_u64 v[0:1], v[2:3], 0, s[22:23]
	v_add_u32_e32 v2, 0x8800, v14
	s_nop 0
	v_readfirstlane_b32 s0, v2
	v_or_b32_e32 v2, 0xc00, v14
	s_mov_b32 m0, s0
	v_readfirstlane_b32 s0, v2
	v_add_u32_e32 v2, 0x8c00, v14
	global_load_lds_dwordx4 v[0:1], off
	v_lshl_add_u64 v[0:1], v[6:7], 0, s[24:25]
	s_mov_b32 m0, s0
	v_readfirstlane_b32 s0, v2
	global_load_lds_dwordx4 v[0:1], off
	v_lshl_add_u64 v[0:1], v[8:9], 0, s[24:25]
	s_mov_b32 m0, s0
	s_mov_b32 s0, 0x10000
	global_load_lds_dwordx4 v[0:1], off
	v_mov_b32_e32 v0, v158
	s_nop 0
	v_and_b32_e32 v1, 15, v0
	v_lshrrev_b32_e32 v2, 4, v0
	v_bfe_u32 v6, v0, 1, 3
	v_bfe_u32 v3, v0, 4, 2
	v_lshlrev_b32_e32 v1, 7, v1
	v_bitop3_b32 v2, v2, v6, 3 bitop3:0x6c
	v_lshl_or_b32 v142, v2, 4, v1
	v_bitop3_b32 v2, v3, v6, 4 bitop3:0x36
	v_lshl_or_b32 v133, v2, 4, v1
	v_lshlrev_b32_e32 v1, 7, v0
	v_lshlrev_b32_e32 v0, 6, v0
	v_and_b32_e32 v143, 0xffffc000, v0
	v_or_b32_e32 v0, s82, v13
	v_add_u32_e32 v0, v0, v12
	v_or_b32_e32 v2, s44, v13
	v_and_b32_e32 v144, 0x6000, v1
	v_ashrrev_i32_e32 v1, 31, v0
	v_add_u32_e32 v2, v2, v12
	v_lshlrev_b64 v[0:1], 11, v[0:1]
	v_ashrrev_i32_e32 v3, 31, v2
	v_or_b32_e32 v0, v0, v128
	v_lshlrev_b64 v[2:3], 11, v[2:3]
	v_lshl_add_u64 v[134:135], s[10:11], 0, v[0:1]
	v_or_b32_e32 v2, v2, v128
	v_lshl_add_u64 v[0:1], v[0:1], 0, v[4:5]
	v_lshl_add_u64 v[138:139], s[10:11], 0, v[0:1]
	v_lshl_add_u64 v[0:1], v[2:3], 0, v[4:5]
	v_lshl_add_u64 v[140:141], s[10:11], 0, v[0:1]
	v_mov_b32_e32 v0, 0
	v_lshl_add_u64 v[136:137], s[10:11], 0, v[2:3]
	v_mov_b32_e32 v1, v0
	v_mov_b32_e32 v2, v0
	v_mov_b32_e32 v3, v0
	v_mov_b32_e32 v4, v0
	v_mov_b32_e32 v5, v0
	v_mov_b32_e32 v6, v0
	v_mov_b32_e32 v7, v0
	v_mov_b32_e32 v8, v0
	v_mov_b32_e32 v9, v0
	v_mov_b32_e32 v10, v0
	v_mov_b32_e32 v11, v0
	v_mov_b32_e32 v12, v0
	v_mov_b32_e32 v13, v0
	v_mov_b32_e32 v14, v0
	v_mov_b32_e32 v15, v0
	v_mov_b32_e32 v16, v0
	v_mov_b32_e32 v17, v0
	v_mov_b32_e32 v18, v0
	v_mov_b32_e32 v19, v0
	v_mov_b32_e32 v20, v0
	v_mov_b32_e32 v21, v0
	v_mov_b32_e32 v22, v0
	v_mov_b32_e32 v23, v0
	v_mov_b32_e32 v24, v0
	v_mov_b32_e32 v25, v0
	v_mov_b32_e32 v26, v0
	v_mov_b32_e32 v27, v0
	v_mov_b32_e32 v28, v0
	v_mov_b32_e32 v29, v0
	v_mov_b32_e32 v30, v0
	v_mov_b32_e32 v31, v0
	v_mov_b32_e32 v32, v0
	v_mov_b32_e32 v33, v0
	v_mov_b32_e32 v34, v0
	v_mov_b32_e32 v35, v0
	v_mov_b32_e32 v36, v0
	v_mov_b32_e32 v37, v0
	v_mov_b32_e32 v38, v0
	v_mov_b32_e32 v39, v0
	v_mov_b32_e32 v40, v0
	v_mov_b32_e32 v41, v0
	v_mov_b32_e32 v42, v0
	v_mov_b32_e32 v43, v0
	v_mov_b32_e32 v44, v0
	v_mov_b32_e32 v45, v0
	v_mov_b32_e32 v46, v0
	v_mov_b32_e32 v47, v0
	v_mov_b32_e32 v48, v0
	v_mov_b32_e32 v49, v0
	v_mov_b32_e32 v50, v0
	v_mov_b32_e32 v51, v0
	v_mov_b32_e32 v52, v0
	v_mov_b32_e32 v53, v0
	v_mov_b32_e32 v54, v0
	v_mov_b32_e32 v55, v0
	v_mov_b32_e32 v56, v0
	v_mov_b32_e32 v57, v0
	v_mov_b32_e32 v58, v0
	v_mov_b32_e32 v59, v0
	v_mov_b32_e32 v60, v0
	v_mov_b32_e32 v61, v0
	v_mov_b32_e32 v62, v0
	v_mov_b32_e32 v63, v0
	v_mov_b32_e32 v64, v0
	v_mov_b32_e32 v65, v0
	v_mov_b32_e32 v66, v0
	v_mov_b32_e32 v67, v0
	v_mov_b32_e32 v68, v0
	v_mov_b32_e32 v69, v0
	v_mov_b32_e32 v70, v0
	v_mov_b32_e32 v71, v0
	v_mov_b32_e32 v72, v0
	v_mov_b32_e32 v73, v0
	v_mov_b32_e32 v74, v0
	v_mov_b32_e32 v75, v0
	v_mov_b32_e32 v76, v0
	v_mov_b32_e32 v77, v0
	v_mov_b32_e32 v78, v0
	v_mov_b32_e32 v79, v0
	v_mov_b32_e32 v80, v0
	v_mov_b32_e32 v81, v0
	v_mov_b32_e32 v82, v0
	v_mov_b32_e32 v83, v0
	v_mov_b32_e32 v84, v0
	v_mov_b32_e32 v85, v0
	v_mov_b32_e32 v86, v0
	v_mov_b32_e32 v87, v0
	v_mov_b32_e32 v88, v0
	v_mov_b32_e32 v89, v0
	v_mov_b32_e32 v90, v0
	v_mov_b32_e32 v91, v0
	v_mov_b32_e32 v92, v0
	v_mov_b32_e32 v93, v0
	v_mov_b32_e32 v94, v0
	v_mov_b32_e32 v95, v0
	v_mov_b32_e32 v96, v0
	v_mov_b32_e32 v97, v0
	v_mov_b32_e32 v98, v0
	v_mov_b32_e32 v99, v0
	v_mov_b32_e32 v100, v0
	v_mov_b32_e32 v101, v0
	v_mov_b32_e32 v102, v0
	v_mov_b32_e32 v103, v0
	v_mov_b32_e32 v104, v0
	v_mov_b32_e32 v105, v0
	v_mov_b32_e32 v106, v0
	v_mov_b32_e32 v107, v0
	v_mov_b32_e32 v108, v0
	v_mov_b32_e32 v109, v0
	v_mov_b32_e32 v110, v0
	v_mov_b32_e32 v111, v0
	v_mov_b32_e32 v112, v0
	v_mov_b32_e32 v113, v0
	v_mov_b32_e32 v114, v0
	v_mov_b32_e32 v115, v0
	v_mov_b32_e32 v116, v0
	v_mov_b32_e32 v117, v0
	v_mov_b32_e32 v118, v0
	v_mov_b32_e32 v119, v0
	v_mov_b32_e32 v120, v0
	v_mov_b32_e32 v121, v0
	v_mov_b32_e32 v122, v0
	v_mov_b32_e32 v123, v0
	v_mov_b32_e32 v124, v0
	v_mov_b32_e32 v125, v0
	v_mov_b32_e32 v126, v0
	v_mov_b32_e32 v127, v0
	.p2alignl 6, 3212836864
	v_lshlrev_b32_e32 v208, 6, v158
	v_and_b32_e32 v208, 0xfffff000, v208
	v_lshlrev_b32_e32 v209, 4, v158
	v_and_or_b32 v208, v209, s50, v208
	s_nop 0
	v_readfirstlane_b32 s86, v208
; __device__ __forceinline__ f32x4 mfma16(bf16x8 a, bf16x8 b, f32x4 c) { return __builtin_amdgcn_mfma_f32_16x16x32_bf16(a, b, c, 0, 0, 0); }
; #define WAIT_V(n) asm volatile("s_waitcnt vmcnt(" #n ")" ::: "memory")
; __device__ __forceinline__ void gemm_mainloop(f32x4 (&acc)[8][4], const GemmSrc& g, int K, char* lds) {
;     ...
;     for (int kt = 0; kt < KT; kt++) {
;         WAIT_V(0);
;         __builtin_amdgcn_s_barrier();
;         const char* st = lds + (kt & 1) * 65536;
;         bf16x8 afA[4], afB[4], bX[4], bY[4];
; #pragma unroll
;         for (int ni = 0; ni < 4; ni++) afA[ni] = *(const bf16x8*)(st + woff + ni * 16 * 128 + rdo0);
; #pragma unroll
;         for (int mi = 0; mi < 4; mi++) bX[mi] = *(const bf16x8*)(st + xoff + mi * 16 * 128 + rdo0);
;         if (kt + 1 < KT) gemm_issue(g, kt + 1, (kt + 1) & 1, lds);
; #pragma unroll
;         for (int mi = 0; mi < 4; mi++) bY[mi] = *(const bf16x8*)(st + xoff + (4 + mi) * 16 * 128 + rdo0);
; #pragma unroll
;         for (int ni = 0; ni < 4; ni++) afB[ni] = *(const bf16x8*)(st + woff + ni * 16 * 128 + rdo1);
; #pragma unroll
;         for (int mi = 0; mi < 4; mi++)
; #pragma unroll
;             for (int ni = 0; ni < 4; ni++) acc[mi][ni] = mfma16(afA[ni], bX[mi], acc[mi][ni]);
;         __builtin_amdgcn_sched_barrier(0);
; #pragma unroll
;         for (int mi = 0; mi < 4; mi++) bX[mi] = *(const bf16x8*)(st + xoff + mi * 16 * 128 + rdo1);
; #pragma unroll
;         for (int mi = 0; mi < 4; mi++)
; #pragma unroll
;             for (int ni = 0; ni < 4; ni++) acc[4 + mi][ni] = mfma16(afA[ni], bY[mi], acc[4 + mi][ni]);
.LBB0_300:
	s_add_i32 s45, s0, 0xffff0000
	s_and_b32 s45, s45, 0x10000
	v_or_b32_e32 v128, s45, v144
	v_add_u32_e32 v145, v128, v142
	s_waitcnt vmcnt(0)
	s_barrier
	ds_read_b128 v[146:149], v145 offset:32768
	ds_read_b128 v[160:163], v145 offset:34816
	ds_read_b128 v[164:167], v145 offset:36864
	ds_read_b128 v[168:171], v145 offset:38912
	v_add_u32_e32 v145, s45, v143
	v_add_u32_e32 v194, v145, v142
	ds_read_b128 v[172:175], v194
	ds_read_b128 v[176:179], v194 offset:2048
	ds_read_b128 v[180:183], v194 offset:4096
	ds_read_b128 v[184:187], v194 offset:6144
	s_waitcnt lgkmcnt(0)
	v_mfma_f32_16x16x32_bf16 v[124:127], v[146:149], v[172:175], v[124:127]
	v_mfma_f32_16x16x32_bf16 v[120:123], v[160:163], v[172:175], v[120:123]
	v_mfma_f32_16x16x32_bf16 v[116:119], v[164:167], v[172:175], v[116:119]
	v_add_u32_e32 v128, v128, v133
	v_mfma_f32_16x16x32_bf16 v[112:115], v[168:171], v[172:175], v[112:115]
	v_mfma_f32_16x16x32_bf16 v[108:111], v[146:149], v[176:179], v[108:111]
	v_mfma_f32_16x16x32_bf16 v[104:107], v[160:163], v[176:179], v[104:107]
	v_mfma_f32_16x16x32_bf16 v[100:103], v[164:167], v[176:179], v[100:103]
	v_mfma_f32_16x16x32_bf16 v[96:99], v[168:171], v[176:179], v[96:99]
	ds_read_b128 v[172:175], v194 offset:8192
	ds_read_b128 v[176:179], v194 offset:10240
	v_mfma_f32_16x16x32_bf16 v[92:95], v[146:149], v[180:183], v[92:95]
	v_mfma_f32_16x16x32_bf16 v[88:91], v[160:163], v[180:183], v[88:91]
	v_mfma_f32_16x16x32_bf16 v[84:87], v[164:167], v[180:183], v[84:87]
	v_mfma_f32_16x16x32_bf16 v[80:83], v[168:171], v[180:183], v[80:83]
	ds_read_b128 v[180:183], v194 offset:12288
	ds_read_b128 v[188:191], v194 offset:14336
	ds_read_b128 v[192:195], v128 offset:32768
	ds_read_b128 v[196:199], v128 offset:34816
	ds_read_b128 v[200:203], v128 offset:36864
	ds_read_b128 v[204:207], v128 offset:38912
	v_mfma_f32_16x16x32_bf16 v[76:79], v[146:149], v[184:187], v[76:79]
	v_mfma_f32_16x16x32_bf16 v[72:75], v[160:163], v[184:187], v[72:75]
	v_mfma_f32_16x16x32_bf16 v[68:71], v[164:167], v[184:187], v[68:71]
	v_mfma_f32_16x16x32_bf16 v[64:67], v[168:171], v[184:187], v[64:67]
	v_add_u32_e32 v128, v145, v133
	s_waitcnt lgkmcnt(0)
	v_mfma_f32_16x16x32_bf16 v[60:63], v[146:149], v[172:175], v[60:63]
	s_and_b32 s46, s0, 0x10000
	s_add_i32 s46, s46, s86
	v_lshl_add_u64 v[208:209], v[134:135], 0, s[8:9]
	s_mov_b32 m0, s46
	v_lshl_add_u64 v[216:217], v[208:209], 0, s[26:27]
	global_load_lds_dwordx4 v[216:217], off
	v_mfma_f32_16x16x32_bf16 v[56:59], v[160:163], v[172:175], v[56:59]
	v_mfma_f32_16x16x32_bf16 v[52:55], v[164:167], v[172:175], v[52:55]
	v_lshl_add_u64 v[210:211], v[136:137], 0, s[8:9]
	s_add_u32 m0, s46, 0x8000
	v_lshl_add_u64 v[218:219], v[210:211], 0, s[28:29]
	global_load_lds_dwordx4 v[218:219], off
	v_mfma_f32_16x16x32_bf16 v[48:51], v[168:171], v[172:175], v[48:51]
	v_mfma_f32_16x16x32_bf16 v[44:47], v[146:149], v[176:179], v[44:47]
	v_lshl_add_u64 v[212:213], v[138:139], 0, s[8:9]
	s_add_u32 m0, s46, 0x400
	v_lshl_add_u64 v[216:217], v[212:213], 0, s[30:31]
	global_load_lds_dwordx4 v[216:217], off
	v_mfma_f32_16x16x32_bf16 v[40:43], v[160:163], v[176:179], v[40:43]
	v_mfma_f32_16x16x32_bf16 v[36:39], v[164:167], v[176:179], v[36:39]
	v_lshl_add_u64 v[214:215], v[140:141], 0, s[8:9]
	s_add_u32 m0, s46, 0x8400
	v_lshl_add_u64 v[218:219], v[214:215], 0, s[34:35]
	global_load_lds_dwordx4 v[218:219], off
	v_mfma_f32_16x16x32_bf16 v[28:31], v[146:149], v[180:183], v[28:31]
	v_mfma_f32_16x16x32_bf16 v[24:27], v[160:163], v[180:183], v[24:27]
	s_add_u32 m0, s46, 0x800
	v_lshl_add_u64 v[216:217], v[208:209], 0, s[36:37]
	global_load_lds_dwordx4 v[216:217], off
	v_mfma_f32_16x16x32_bf16 v[20:23], v[164:167], v[180:183], v[20:23]
	v_mfma_f32_16x16x32_bf16 v[12:15], v[146:149], v[188:191], v[12:15]
	s_add_u32 m0, s46, 0x8800
	v_lshl_add_u64 v[218:219], v[210:211], 0, s[38:39]
	global_load_lds_dwordx4 v[218:219], off
	v_mfma_f32_16x16x32_bf16 v[8:11], v[160:163], v[188:191], v[8:11]
	v_mfma_f32_16x16x32_bf16 v[4:7], v[164:167], v[188:191], v[4:7]
	s_add_u32 m0, s46, 0xc00
	v_lshl_add_u64 v[216:217], v[212:213], 0, s[40:41]
	global_load_lds_dwordx4 v[216:217], off
	ds_read_b128 v[146:149], v128
	ds_read_b128 v[160:163], v128 offset:2048
	ds_read_b128 v[164:167], v128 offset:4096
	ds_read_b128 v[172:175], v128 offset:6144
	v_mfma_f32_16x16x32_bf16 v[32:35], v[168:171], v[176:179], v[32:35]
	v_mfma_f32_16x16x32_bf16 v[16:19], v[168:171], v[180:183], v[16:19]
	s_add_u32 m0, s46, 0x8c00
	v_lshl_add_u64 v[218:219], v[214:215], 0, s[42:43]
	global_load_lds_dwordx4 v[218:219], off
	v_mfma_f32_16x16x32_bf16 v[0:3], v[168:171], v[188:191], v[0:3]
	s_waitcnt lgkmcnt(0)
	v_mfma_f32_16x16x32_bf16 v[124:127], v[192:195], v[146:149], v[124:127]
	v_mfma_f32_16x16x32_bf16 v[120:123], v[196:199], v[146:149], v[120:123]
	v_mfma_f32_16x16x32_bf16 v[116:119], v[200:203], v[146:149], v[116:119]
	v_mfma_f32_16x16x32_bf16 v[112:115], v[204:207], v[146:149], v[112:115]
	v_mfma_f32_16x16x32_bf16 v[108:111], v[192:195], v[160:163], v[108:111]
	v_mfma_f32_16x16x32_bf16 v[104:107], v[196:199], v[160:163], v[104:107]
	v_mfma_f32_16x16x32_bf16 v[100:103], v[200:203], v[160:163], v[100:103]
	v_mfma_f32_16x16x32_bf16 v[96:99], v[204:207], v[160:163], v[96:99]
	v_mfma_f32_16x16x32_bf16 v[92:95], v[192:195], v[164:167], v[92:95]
	v_mfma_f32_16x16x32_bf16 v[88:91], v[196:199], v[164:167], v[88:91]
	v_mfma_f32_16x16x32_bf16 v[84:87], v[200:203], v[164:167], v[84:87]
	v_mfma_f32_16x16x32_bf16 v[80:83], v[204:207], v[164:167], v[80:83]
	ds_read_b128 v[146:149], v128 offset:8192
	ds_read_b128 v[160:163], v128 offset:10240
	ds_read_b128 v[164:167], v128 offset:12288
	ds_read_b128 v[168:171], v128 offset:14336
	v_mfma_f32_16x16x32_bf16 v[76:79], v[192:195], v[172:175], v[76:79]
	v_mfma_f32_16x16x32_bf16 v[72:75], v[196:199], v[172:175], v[72:75]
	v_mfma_f32_16x16x32_bf16 v[68:71], v[200:203], v[172:175], v[68:71]
	v_mfma_f32_16x16x32_bf16 v[64:67], v[204:207], v[172:175], v[64:67]
	s_waitcnt lgkmcnt(0)
; __device__ __forceinline__ f32x4 mfma16(bf16x8 a, bf16x8 b, f32x4 c) { return __builtin_amdgcn_mfma_f32_16x16x32_bf16(a, b, c, 0, 0, 0); }
; __device__ __forceinline__ void gemm_mainloop(f32x4 (&acc)[8][4], const GemmSrc& g, int K, char* lds) {
;     ...
;         for (int mi = 0; mi < 4; mi++) bX[mi] = *(const bf16x8*)(st + xoff + mi * 16 * 128 + rdo1);
; #pragma unroll
;         for (int mi = 0; mi < 4; mi++)
; #pragma unroll
;             for (int ni = 0; ni < 4; ni++) acc[4 + mi][ni] = mfma16(afA[ni], bY[mi], acc[4 + mi][ni]);
;         __builtin_amdgcn_sched_barrier(0);
; #pragma unroll
;         for (int mi = 0; mi < 4; mi++) bY[mi] = *(const bf16x8*)(st + xoff + (4 + mi) * 16 * 128 + rdo1);
; #pragma unroll
;         for (int mi = 0; mi < 4; mi++)
; #pragma unroll
;             for (int ni = 0; ni < 4; ni++) acc[mi][ni] = mfma16(afB[ni], bX[mi], acc[mi][ni]);
;         __builtin_amdgcn_sched_barrier(0);
; #pragma unroll
;         for (int mi = 0; mi < 4; mi++)
; #pragma unroll
;             for (int ni = 0; ni < 4; ni++) acc[4 + mi][ni] = mfma16(afB[ni], bY[mi], acc[4 + mi][ni]);
;         __builtin_amdgcn_sched_barrier(0);
;     }
	v_mfma_f32_16x16x32_bf16 v[60:63], v[192:195], v[146:149], v[60:63]
	v_mfma_f32_16x16x32_bf16 v[56:59], v[196:199], v[146:149], v[56:59]
	v_mfma_f32_16x16x32_bf16 v[52:55], v[200:203], v[146:149], v[52:55]
	v_mfma_f32_16x16x32_bf16 v[48:51], v[204:207], v[146:149], v[48:51]
	v_mfma_f32_16x16x32_bf16 v[44:47], v[192:195], v[160:163], v[44:47]
	v_mfma_f32_16x16x32_bf16 v[40:43], v[196:199], v[160:163], v[40:43]
	v_mfma_f32_16x16x32_bf16 v[36:39], v[200:203], v[160:163], v[36:39]
	v_mfma_f32_16x16x32_bf16 v[32:35], v[204:207], v[160:163], v[32:35]
	v_mfma_f32_16x16x32_bf16 v[28:31], v[192:195], v[164:167], v[28:31]
	v_mfma_f32_16x16x32_bf16 v[24:27], v[196:199], v[164:167], v[24:27]
	v_mfma_f32_16x16x32_bf16 v[20:23], v[200:203], v[164:167], v[20:23]
	v_mfma_f32_16x16x32_bf16 v[16:19], v[204:207], v[164:167], v[16:19]
	v_mfma_f32_16x16x32_bf16 v[12:15], v[192:195], v[168:171], v[12:15]
	v_mfma_f32_16x16x32_bf16 v[8:11], v[196:199], v[168:171], v[8:11]
	v_mfma_f32_16x16x32_bf16 v[4:7], v[200:203], v[168:171], v[4:7]
	v_mfma_f32_16x16x32_bf16 v[0:3], v[204:207], v[168:171], v[0:3]
	s_add_u32 s8, s8, 0x80
	s_addc_u32 s9, s9, 0
	s_add_i32 s0, s0, 0x10000
	s_cmpk_lg_i32 s8, 0x780
	s_cbranch_scc1 .LBB0_300
	v_or_b32_e32 v128, 0x8000, v144
	v_add_u32_e32 v151, 0x10000, v143
	v_add3_u32 v150, v128, v142, s52
	v_add_u32_e32 v192, v151, v142
	s_waitcnt vmcnt(0)
	s_barrier
	ds_read_b128 v[134:137], v150
	ds_read_b128 v[138:141], v150 offset:2048
	ds_read_b128 v[142:145], v192
	ds_read_b128 v[146:149], v192 offset:2048
	ds_read_b128 v[160:163], v150 offset:4096
	ds_read_b128 v[164:167], v150 offset:6144
	s_waitcnt lgkmcnt(0)
	v_mfma_f32_16x16x32_bf16 v[124:127], v[134:137], v[142:145], v[124:127]
	v_add3_u32 v128, v128, v133, s52
	v_mfma_f32_16x16x32_bf16 v[120:123], v[138:141], v[142:145], v[120:123]
	v_mfma_f32_16x16x32_bf16 v[116:119], v[160:163], v[142:145], v[116:119]
	v_mfma_f32_16x16x32_bf16 v[112:115], v[164:167], v[142:145], v[112:115]
	v_mfma_f32_16x16x32_bf16 v[108:111], v[134:137], v[146:149], v[108:111]
	v_mfma_f32_16x16x32_bf16 v[104:107], v[138:141], v[146:149], v[104:107]
	v_mfma_f32_16x16x32_bf16 v[100:103], v[160:163], v[146:149], v[100:103]
	v_mfma_f32_16x16x32_bf16 v[96:99], v[164:167], v[146:149], v[96:99]
	ds_read_b128 v[142:145], v192 offset:4096
	ds_read_b128 v[146:149], v192 offset:6144
	s_waitcnt lgkmcnt(0)
	v_mfma_f32_16x16x32_bf16 v[92:95], v[134:137], v[142:145], v[92:95]
	v_mfma_f32_16x16x32_bf16 v[88:91], v[138:141], v[142:145], v[88:91]
	v_mfma_f32_16x16x32_bf16 v[84:87], v[160:163], v[142:145], v[84:87]
	v_mfma_f32_16x16x32_bf16 v[80:83], v[164:167], v[142:145], v[80:83]
	ds_read_b128 v[142:145], v128 offset:6144
	ds_read_b128 v[168:171], v128 offset:4096
	ds_read_b128 v[172:175], v128 offset:2048
	ds_read_b128 v[176:179], v128
	ds_read_b128 v[180:183], v192 offset:14336
	ds_read_b128 v[184:187], v192 offset:12288
	ds_read_b128 v[188:191], v192 offset:10240
	ds_read_b128 v[192:195], v192 offset:8192
	v_mfma_f32_16x16x32_bf16 v[76:79], v[134:137], v[146:149], v[76:79]
	v_mfma_f32_16x16x32_bf16 v[72:75], v[138:141], v[146:149], v[72:75]
	v_mfma_f32_16x16x32_bf16 v[68:71], v[160:163], v[146:149], v[68:71]
	v_mfma_f32_16x16x32_bf16 v[64:67], v[164:167], v[146:149], v[64:67]
	v_add_u32_e32 v128, v151, v133
	s_waitcnt lgkmcnt(0)
	v_mfma_f32_16x16x32_bf16 v[60:63], v[134:137], v[192:195], v[60:63]
	v_mfma_f32_16x16x32_bf16 v[56:59], v[138:141], v[192:195], v[56:59]
	v_mfma_f32_16x16x32_bf16 v[52:55], v[160:163], v[192:195], v[52:55]
	v_mfma_f32_16x16x32_bf16 v[44:47], v[134:137], v[188:191], v[44:47]
	v_mfma_f32_16x16x32_bf16 v[40:43], v[138:141], v[188:191], v[40:43]
	v_mfma_f32_16x16x32_bf16 v[36:39], v[160:163], v[188:191], v[36:39]
	v_mfma_f32_16x16x32_bf16 v[28:31], v[134:137], v[184:187], v[28:31]
	v_mfma_f32_16x16x32_bf16 v[24:27], v[138:141], v[184:187], v[24:27]
	v_mfma_f32_16x16x32_bf16 v[20:23], v[160:163], v[184:187], v[20:23]
	v_mfma_f32_16x16x32_bf16 v[12:15], v[134:137], v[180:183], v[12:15]
	v_mfma_f32_16x16x32_bf16 v[8:11], v[138:141], v[180:183], v[8:11]
	v_mfma_f32_16x16x32_bf16 v[4:7], v[160:163], v[180:183], v[4:7]
	ds_read_b128 v[134:137], v128
	ds_read_b128 v[138:141], v128 offset:2048
	ds_read_b128 v[146:149], v128 offset:4096
	ds_read_b128 v[160:163], v128 offset:6144
	v_mfma_f32_16x16x32_bf16 v[48:51], v[164:167], v[192:195], v[48:51]
	v_mfma_f32_16x16x32_bf16 v[32:35], v[164:167], v[188:191], v[32:35]
	v_mfma_f32_16x16x32_bf16 v[16:19], v[164:167], v[184:187], v[16:19]
	v_mfma_f32_16x16x32_bf16 v[0:3], v[164:167], v[180:183], v[0:3]
	s_waitcnt lgkmcnt(0)
; __device__ __forceinline__ f32x4 mfma16(bf16x8 a, bf16x8 b, f32x4 c) { return __builtin_amdgcn_mfma_f32_16x16x32_bf16(a, b, c, 0, 0, 0); }
; __device__ __forceinline__ void gemm_mainloop(f32x4 (&acc)[8][4], const GemmSrc& g, int K, char* lds) {
;     ...
;         for (int mi = 0; mi < 4; mi++)
; #pragma unroll
;             for (int ni = 0; ni < 4; ni++) acc[4 + mi][ni] = mfma16(afB[ni], bY[mi], acc[4 + mi][ni]);
; __device__ void phaseC(const Params& p, char* lds) {
;     ...
;         const int c0 = n0 + wc * 64;
;         const bool isq = (c0 >= ZQ_N && c0 < ZKC);
;         const bool rope = isq || (c0 >= ZKC && c0 < ZGATE && ((c0 - ZKC) & 255) < 128);
;         const float scl = isq ? 0.18033688011112042f : 1.f;
; #pragma unroll
;         for (int mi = 0; mi < 8; mi++) {
;             const int tok = m0 + wr * 128 + mi * 16 + r;
;             if (rope) {
;                 f32x4 v = acc[mi][0];
;                 f32x4 pr;
; #pragma unroll
;                 for (int j = 0; j < 4; j++) pr[j] = __shfl_xor(v[j], 32, 64);
;                 const int ib = (q & 1) * 4;
;                 const f32x4 k0 = *(const f32x4*)(cs + (size_t)tok * 16 + ib * 2);
;                 const f32x4 k1 = *(const f32x4*)(cs + (size_t)tok * 16 + ib * 2 + 4);
;                 const float cc[4] = {k0[0], k0[2], k1[0], k1[2]}, sn[4] = {k0[1], k0[3], k1[1], k1[3]};
; #pragma unroll
;                 for (int j = 0; j < 4; j++) v[j] = (q < 2) ? (v[j] * cc[j] - pr[j] * sn[j]) : (v[j] * cc[j] + pr[j] * sn[j]);
;                 acc[mi][0] = v;
	v_mfma_f32_16x16x32_bf16 v[124:127], v[176:179], v[134:137], v[124:127]
	v_mfma_f32_16x16x32_bf16 v[120:123], v[172:175], v[134:137], v[120:123]
	v_mfma_f32_16x16x32_bf16 v[116:119], v[168:171], v[134:137], v[116:119]
	v_mfma_f32_16x16x32_bf16 v[112:115], v[142:145], v[134:137], v[112:115]
	v_mfma_f32_16x16x32_bf16 v[108:111], v[176:179], v[138:141], v[108:111]
	v_mfma_f32_16x16x32_bf16 v[104:107], v[172:175], v[138:141], v[104:107]
	v_mfma_f32_16x16x32_bf16 v[100:103], v[168:171], v[138:141], v[100:103]
	v_mfma_f32_16x16x32_bf16 v[96:99], v[142:145], v[138:141], v[96:99]
	v_mfma_f32_16x16x32_bf16 v[92:95], v[176:179], v[146:149], v[92:95]
	v_mfma_f32_16x16x32_bf16 v[88:91], v[172:175], v[146:149], v[88:91]
	v_mfma_f32_16x16x32_bf16 v[84:87], v[168:171], v[146:149], v[84:87]
	v_mfma_f32_16x16x32_bf16 v[80:83], v[142:145], v[146:149], v[80:83]
	ds_read_b128 v[134:137], v128 offset:8192
	ds_read_b128 v[138:141], v128 offset:10240
	ds_read_b128 v[146:149], v128 offset:12288
	ds_read_b128 v[164:167], v128 offset:14336
	v_mfma_f32_16x16x32_bf16 v[76:79], v[176:179], v[160:163], v[76:79]
	v_mfma_f32_16x16x32_bf16 v[72:75], v[172:175], v[160:163], v[72:75]
	v_mfma_f32_16x16x32_bf16 v[68:71], v[168:171], v[160:163], v[68:71]
	v_mfma_f32_16x16x32_bf16 v[64:67], v[142:145], v[160:163], v[64:67]
	s_waitcnt lgkmcnt(0)
	v_mfma_f32_16x16x32_bf16 v[60:63], v[176:179], v[134:137], v[60:63]
	v_mfma_f32_16x16x32_bf16 v[56:59], v[172:175], v[134:137], v[56:59]
	v_mfma_f32_16x16x32_bf16 v[52:55], v[168:171], v[134:137], v[52:55]
	v_mfma_f32_16x16x32_bf16 v[48:51], v[142:145], v[134:137], v[48:51]
	v_mfma_f32_16x16x32_bf16 v[44:47], v[176:179], v[138:141], v[44:47]
	v_mfma_f32_16x16x32_bf16 v[40:43], v[172:175], v[138:141], v[40:43]
	v_mfma_f32_16x16x32_bf16 v[36:39], v[168:171], v[138:141], v[36:39]
	v_mfma_f32_16x16x32_bf16 v[32:35], v[142:145], v[138:141], v[32:35]
	v_mfma_f32_16x16x32_bf16 v[28:31], v[176:179], v[146:149], v[28:31]
	v_mfma_f32_16x16x32_bf16 v[24:27], v[172:175], v[146:149], v[24:27]
	v_mfma_f32_16x16x32_bf16 v[20:23], v[168:171], v[146:149], v[20:23]
	v_mfma_f32_16x16x32_bf16 v[16:19], v[142:145], v[146:149], v[16:19]
	v_mfma_f32_16x16x32_bf16 v[12:15], v[176:179], v[164:167], v[12:15]
	v_mfma_f32_16x16x32_bf16 v[8:11], v[172:175], v[164:167], v[8:11]
	v_mfma_f32_16x16x32_bf16 v[4:7], v[168:171], v[164:167], v[4:7]
	v_mfma_f32_16x16x32_bf16 v[0:3], v[142:145], v[164:167], v[0:3]
	s_and_b32 s0, s75, 0xfffffc
	s_cmp_eq_u32 s0, 12
	s_cselect_b64 vcc, -1, 0
	s_add_i32 s0, s44, 0xfffff000
	s_cmpk_lt_u32 s0, 0x300
	s_cselect_b64 s[8:9], -1, 0
	s_and_b64 s[8:9], s[8:9], s[4:5]
	s_or_b64 s[46:47], vcc, s[8:9]
	v_add_u32_e32 v136, s82, v153
	s_waitcnt vmcnt(0)
	s_barrier
	s_and_saveexec_b64 s[48:49], s[46:47]
	s_cbranch_execz .LBB0_303
	v_ashrrev_i32_e32 v137, 31, v136
	v_lshlrev_b64 v[134:135], 6, v[136:137]
	v_lshl_add_u64 v[134:135], v[130:131], 0, v[134:135]
	global_load_dwordx4 v[138:141], v[134:135], off
	global_load_dwordx4 v[142:145], v[134:135], off offset:16
	v_and_b32_e32 v133, 64, v159
	v_xor_b32_e32 v128, 32, v159
	v_add_u32_e32 v133, 64, v133
	v_cmp_lt_i32_e64 s[8:9], v128, v133
	s_waitcnt vmcnt(1)
	v_mov_b32_e32 v149, v140
	v_cndmask_b32_e64 v128, v159, v128, s[8:9]
	v_lshlrev_b32_e32 v128, 2, v128
	ds_bpermute_b32 v134, v128, v124
	ds_bpermute_b32 v135, v128, v125
	ds_bpermute_b32 v146, v128, v126
	ds_bpermute_b32 v147, v128, v127
	v_mov_b32_e32 v140, v139
	s_waitcnt vmcnt(0)
	v_mov_b32_e32 v139, v144
	v_mov_b32_e32 v144, v143
	s_waitcnt lgkmcnt(2)
	v_pk_mul_f32 v[134:135], v[140:141], v[134:135]
	s_waitcnt lgkmcnt(0)
	v_pk_mul_f32 v[140:141], v[144:145], v[146:147]
	v_mov_b32_e32 v148, v138
	v_mov_b32_e32 v138, v142
	v_cndmask_b32_e64 v135, v135, -v135, s[6:7]
	v_cndmask_b32_e64 v134, v134, -v134, s[6:7]
	v_cndmask_b32_e64 v141, v141, -v141, s[6:7]
	v_cndmask_b32_e64 v140, v140, -v140, s[6:7]
	v_pk_fma_f32 v[124:125], v[124:125], v[148:149], v[134:135]
	v_pk_fma_f32 v[126:127], v[126:127], v[138:139], v[140:141]
